# ml_state chunk loop: state-update section re-emitted with the LDS reads of the next 32-row step in flight (two register sets, counted lgkmcnt) instead of read-wait-use per fragment
# speedup vs baseline: 1.0048x; 1.0033x over previous
.LBB0_456:
	s_or_b64 exec, exec, s[42:43]
	v_sub_f32_e32 v61, v61, v65
	v_mul_f32_e32 v61, 0x3fb8aa3b, v61
	v_exp_f32_e32 v64, v61
	v_cvt_pk_bf16_f32 v61, v20, v161
	global_store_short v[56:57], v61, off offset:-512
	v_cvt_pk_bf16_f32 v61, v105, v161
	global_store_short v[56:57], v61, off offset:-256
	v_cvt_pk_bf16_f32 v61, v106, v161
	global_store_short v[56:57], v61, off
	v_cvt_pk_bf16_f32 v61, v107, v161
	v_or_b32_e32 v106, 0x1000, v54
	v_mov_b32_e32 v107, v55
	global_store_short v[56:57], v61, off offset:256
	v_cvt_pk_bf16_f32 v61, v108, v161
	v_lshl_add_u64 v[106:107], v[32:33], 0, v[106:107]
	global_store_short v[106:107], v61, off
	v_cvt_pk_bf16_f32 v61, v104, v161
	v_or_b32_e32 v104, 0x1100, v54
	v_mov_b32_e32 v105, v55
	v_lshl_add_u64 v[104:105], v[32:33], 0, v[104:105]
	global_store_short v[104:105], v61, off
	v_or_b32_e32 v104, 0x1200, v54
	v_mov_b32_e32 v105, v55
	v_cvt_pk_bf16_f32 v61, v103, v161
	v_lshl_add_u64 v[104:105], v[32:33], 0, v[104:105]
	global_store_short v[104:105], v61, off
	v_cvt_pk_bf16_f32 v61, v102, v161
	v_or_b32_e32 v102, 0x1300, v54
	v_mov_b32_e32 v103, v55
	v_lshl_add_u64 v[102:103], v[32:33], 0, v[102:103]
	global_store_short v[102:103], v61, off
	s_waitcnt lgkmcnt(0)
	v_lshl_add_u32 v61, v75, 1, s44
	v_add_u32_e32 v62, v61, v77
	v_add_u32_e32 v61, v61, v84
	ds_read_b128 v[176:179], v76
	ds_read_b128 v[180:183], v76 offset:16
	ds_read_b128 v[184:187], v62 offset:4096
	ds_read_b128 v[196:199], v61 offset:38912
	ds_read_b128 v[200:203], v61 offset:43264
	ds_read_b128 v[238:241], v76 offset:128
	ds_read_b128 v[242:245], v76 offset:144
	ds_read_b128 v[246:249], v62 offset:4160
	ds_read_b128 v[206:209], v61 offset:38976
	ds_read_b128 v[210:213], v61 offset:43328
	v_pk_mul_f32 v[20:21], v[20:21], v[64:65] op_sel_hi:[1,0]
	v_pk_mul_f32 v[22:23], v[22:23], v[64:65] op_sel_hi:[1,0]
	v_pk_mul_f32 v[24:25], v[24:25], v[64:65] op_sel_hi:[1,0]
	v_pk_mul_f32 v[26:27], v[26:27], v[64:65] op_sel_hi:[1,0]
	s_waitcnt lgkmcnt(7)
	v_lshlrev_b32_e32 v110, 16, v184
	v_and_b32_e32 v111, 0xffff0000, v184
	v_lshlrev_b32_e32 v112, 16, v185
	v_and_b32_e32 v113, 0xffff0000, v185
	v_lshlrev_b32_e32 v114, 16, v186
	v_and_b32_e32 v115, 0xffff0000, v186
	v_lshlrev_b32_e32 v116, 16, v187
	v_and_b32_e32 v117, 0xffff0000, v187
	v_mul_f32_e32 v102, v176, v110
	v_mul_f32_e32 v103, v177, v111
	v_mul_f32_e32 v104, v178, v112
	v_mul_f32_e32 v105, v179, v113
	v_fma_f32 v118, v180, v114, v102
	v_fma_f32 v108, v181, v115, v103
	v_fma_f32 v109, v182, v116, v104
	v_fma_f32 v110, v183, v117, v105
	v_mul_f32_e32 v106, v180, v114
	v_mul_f32_e32 v107, v181, v115
	v_mul_f32_e32 v114, v182, v116
	v_mul_f32_e32 v115, v183, v117
	v_cvt_pk_bf16_f32 v102, v102, v103
	v_cvt_pk_bf16_f32 v103, v104, v105
	v_cvt_pk_bf16_f32 v104, v106, v107
	v_cvt_pk_bf16_f32 v105, v114, v115
	s_waitcnt lgkmcnt(6)
	s_nop 1
	v_mfma_f32_16x16x32_bf16 v[20:23], v[196:199], v[102:105], v[20:23]
	s_waitcnt lgkmcnt(5)
	v_mfma_f32_16x16x32_bf16 v[24:27], v[200:203], v[102:105], v[24:27]
	v_add_f32_e32 v119, 0, v118
	v_add_f32_e32 v119, v108, v119
	v_add_f32_e32 v119, v109, v119
	v_add_f32_e32 v119, v110, v119
	ds_read_b128 v[176:179], v76 offset:256
	ds_read_b128 v[180:183], v76 offset:272
	ds_read_b128 v[184:187], v62 offset:4224
	ds_read_b128 v[196:199], v61 offset:39040
	ds_read_b128 v[200:203], v61 offset:43392
	s_waitcnt lgkmcnt(7)
	v_lshlrev_b32_e32 v110, 16, v246
	v_and_b32_e32 v111, 0xffff0000, v246
	v_lshlrev_b32_e32 v112, 16, v247
	v_and_b32_e32 v113, 0xffff0000, v247
	v_lshlrev_b32_e32 v114, 16, v248
	v_and_b32_e32 v115, 0xffff0000, v248
	v_lshlrev_b32_e32 v116, 16, v249
	v_and_b32_e32 v117, 0xffff0000, v249
	v_mul_f32_e32 v102, v238, v110
	v_mul_f32_e32 v103, v239, v111
	v_mul_f32_e32 v104, v240, v112
	v_mul_f32_e32 v105, v241, v113
	v_fma_f32 v118, v242, v114, v102
	v_fma_f32 v108, v243, v115, v103
	v_fma_f32 v109, v244, v116, v104
	v_fma_f32 v110, v245, v117, v105
	v_mul_f32_e32 v106, v242, v114
	v_mul_f32_e32 v107, v243, v115
	v_mul_f32_e32 v114, v244, v116
	v_mul_f32_e32 v115, v245, v117
	v_cvt_pk_bf16_f32 v102, v102, v103
	v_cvt_pk_bf16_f32 v103, v104, v105
	v_cvt_pk_bf16_f32 v104, v106, v107
	v_cvt_pk_bf16_f32 v105, v114, v115
	s_waitcnt lgkmcnt(6)
	s_nop 1
	v_mfma_f32_16x16x32_bf16 v[20:23], v[206:209], v[102:105], v[20:23]
	s_waitcnt lgkmcnt(5)
	v_mfma_f32_16x16x32_bf16 v[24:27], v[210:213], v[102:105], v[24:27]
	v_add_f32_e32 v119, v119, v118
	v_add_f32_e32 v119, v108, v119
	v_add_f32_e32 v119, v109, v119
	v_add_f32_e32 v119, v110, v119
	ds_read_b128 v[238:241], v76 offset:384
	ds_read_b128 v[242:245], v76 offset:400
	ds_read_b128 v[246:249], v62 offset:4288
	ds_read_b128 v[206:209], v61 offset:39104
	ds_read_b128 v[210:213], v61 offset:43456
	s_waitcnt lgkmcnt(7)
	v_lshlrev_b32_e32 v110, 16, v184
	v_and_b32_e32 v111, 0xffff0000, v184
	v_lshlrev_b32_e32 v112, 16, v185
	v_and_b32_e32 v113, 0xffff0000, v185
	v_lshlrev_b32_e32 v114, 16, v186
	v_and_b32_e32 v115, 0xffff0000, v186
	v_lshlrev_b32_e32 v116, 16, v187
	v_and_b32_e32 v117, 0xffff0000, v187
	v_mul_f32_e32 v102, v176, v110
	v_mul_f32_e32 v103, v177, v111
	v_mul_f32_e32 v104, v178, v112
	v_mul_f32_e32 v105, v179, v113
	v_fma_f32 v118, v180, v114, v102
	v_fma_f32 v108, v181, v115, v103
	v_fma_f32 v109, v182, v116, v104
	v_fma_f32 v110, v183, v117, v105
	v_mul_f32_e32 v106, v180, v114
	v_mul_f32_e32 v107, v181, v115
	v_mul_f32_e32 v114, v182, v116
	v_mul_f32_e32 v115, v183, v117
	v_cvt_pk_bf16_f32 v102, v102, v103
	v_cvt_pk_bf16_f32 v103, v104, v105
	v_cvt_pk_bf16_f32 v104, v106, v107
	v_cvt_pk_bf16_f32 v105, v114, v115
	s_waitcnt lgkmcnt(6)
	s_nop 1
	v_mfma_f32_16x16x32_bf16 v[20:23], v[196:199], v[102:105], v[20:23]
	s_waitcnt lgkmcnt(5)
	v_mfma_f32_16x16x32_bf16 v[24:27], v[200:203], v[102:105], v[24:27]
	v_add_f32_e32 v119, v119, v118
	v_add_f32_e32 v119, v108, v119
	v_add_f32_e32 v119, v109, v119
	v_add_f32_e32 v119, v110, v119
	s_waitcnt lgkmcnt(2)
	v_lshlrev_b32_e32 v110, 16, v246
	v_and_b32_e32 v111, 0xffff0000, v246
	v_lshlrev_b32_e32 v112, 16, v247
	v_and_b32_e32 v113, 0xffff0000, v247
	v_lshlrev_b32_e32 v114, 16, v248
	v_and_b32_e32 v115, 0xffff0000, v248
	v_lshlrev_b32_e32 v116, 16, v249
	v_and_b32_e32 v117, 0xffff0000, v249
	v_mul_f32_e32 v102, v238, v110
	v_mul_f32_e32 v103, v239, v111
	v_mul_f32_e32 v104, v240, v112
	v_mul_f32_e32 v105, v241, v113
	v_fma_f32 v118, v242, v114, v102
	v_fma_f32 v108, v243, v115, v103
	v_fma_f32 v109, v244, v116, v104
	v_fma_f32 v110, v245, v117, v105
	v_mul_f32_e32 v106, v242, v114
	v_mul_f32_e32 v107, v243, v115
	v_mul_f32_e32 v114, v244, v116
	v_mul_f32_e32 v115, v245, v117
	v_cvt_pk_bf16_f32 v102, v102, v103
	v_cvt_pk_bf16_f32 v103, v104, v105
	v_cvt_pk_bf16_f32 v104, v106, v107
	v_cvt_pk_bf16_f32 v105, v114, v115
	s_waitcnt lgkmcnt(1)
	s_nop 1
	v_mfma_f32_16x16x32_bf16 v[20:23], v[206:209], v[102:105], v[20:23]
	s_waitcnt lgkmcnt(0)
	v_mfma_f32_16x16x32_bf16 v[24:27], v[210:213], v[102:105], v[24:27]
	v_add_f32_e32 v119, v119, v118
	v_add_f32_e32 v119, v108, v119
	v_add_f32_e32 v119, v109, v119
	v_add_f32_e32 v61, v110, v119
	ds_bpermute_b32 v62, v98, v61
	s_waitcnt lgkmcnt(0)
	v_add_f32_e32 v61, v61, v62
	ds_bpermute_b32 v62, v99, v61
	s_andn2_b64 vcc, exec, s[40:41]
	s_cbranch_vccnz .LBB0_446
	s_bitcmp1_b32 s24, 0
	s_cselect_b32 s40, 0xae00, 0
	s_add_i32 s42, s40, 0
	v_add_u32_e32 v102, s42, v73
	v_add_u32_e32 v103, s42, v81
	s_bitcmp1_b32 s24, 0
	s_cbranch_scc0 .Lmls_stA
	s_cmp_lg_u64 s[34:35], 0
	s_cbranch_scc0 .Lmls_genB
	s_cmp_eq_u32 s24, 1
	s_cbranch_scc1 .Lmls_w0aB
	s_cmp_eq_u32 s24, 33
	s_cbranch_scc1 .Lmls_w0cB
	s_waitcnt vmcnt(41)
	ds_write_b128 v102, v[120:123] offset:4096
	s_waitcnt vmcnt(40)
	ds_write_b128 v103, v[124:127] offset:4096
	v_add_u32_e32 v103, s42, v82
	s_waitcnt vmcnt(39)
	ds_write_b128 v103, v[128:131] offset:4096
	v_add_u32_e32 v103, s42, v83
	s_waitcnt vmcnt(38)
	ds_write_b128 v103, v[132:135] offset:4096
	s_waitcnt vmcnt(37)
	ds_write_b128 v102, v[136:139] offset:38912
	s_branch .Lmls_ldB
